# dropped the redundant s_nop after tile staging in the softmax segment (staging block already separates the QK MFMAs from the first S read)
# speedup vs baseline: 1.0132x; 1.0132x over previous
; __device__ __forceinline__ void attn_unit(KParams& P, int l, const AUnit& U, LAS unsigned char* lds) {
;     ...
;         if ((t + 1) * 64 > U.kvlen) {
;             const int kb0 = t * 64 + 8 * hi;
; #pragma unroll
;             for (int r = 0; r < 16; ++r) { const int kv = kb0 + 16 * (r >> 3) + (r & 7); if (kv >= U.kvlen) p0[r] = -INFINITY; if (kv + 32 >= U.kvlen) p1[r] = -INFINITY; }
;         }
.Lattn_noload_y:
	s_lshl_b32 s25, s20, 6
	s_add_i32 s28, s25, 64
	s_cmp_le_u32 s28, s70
	s_cbranch_scc1 .Lattn_nomask
	v_add_u32_e32 v208, s25, v164
	v_add_u32_e32 v209, 0, v208
	v_cmp_gt_u32_e32 vcc, s70, v209
	s_nop 1
	v_cndmask_b32_e32 v80, v225, v80, vcc
	v_add_u32_e32 v209, 32, v208
	v_cmp_gt_u32_e32 vcc, s70, v209
	s_nop 1
	v_cndmask_b32_e32 v64, v225, v64, vcc
	v_add_u32_e32 v209, 1, v208
	v_cmp_gt_u32_e32 vcc, s70, v209
	s_nop 1
	v_cndmask_b32_e32 v81, v225, v81, vcc
	v_add_u32_e32 v209, 33, v208
	v_cmp_gt_u32_e32 vcc, s70, v209
	s_nop 1
	v_cndmask_b32_e32 v65, v225, v65, vcc
	v_add_u32_e32 v209, 2, v208
	v_cmp_gt_u32_e32 vcc, s70, v209
	s_nop 1
	v_cndmask_b32_e32 v82, v225, v82, vcc
	v_add_u32_e32 v209, 34, v208
	v_cmp_gt_u32_e32 vcc, s70, v209
	s_nop 1
	v_cndmask_b32_e32 v66, v225, v66, vcc
	v_add_u32_e32 v209, 3, v208
	v_cmp_gt_u32_e32 vcc, s70, v209
	s_nop 1
	v_cndmask_b32_e32 v83, v225, v83, vcc
	v_add_u32_e32 v209, 35, v208
	v_cmp_gt_u32_e32 vcc, s70, v209
	s_nop 1
	v_cndmask_b32_e32 v67, v225, v67, vcc
	v_add_u32_e32 v209, 4, v208
	v_cmp_gt_u32_e32 vcc, s70, v209
	s_nop 1
	v_cndmask_b32_e32 v84, v225, v84, vcc
	v_add_u32_e32 v209, 36, v208
	v_cmp_gt_u32_e32 vcc, s70, v209
	s_nop 1
	v_cndmask_b32_e32 v68, v225, v68, vcc
	v_add_u32_e32 v209, 5, v208
	v_cmp_gt_u32_e32 vcc, s70, v209
	s_nop 1
	v_cndmask_b32_e32 v85, v225, v85, vcc
	v_add_u32_e32 v209, 37, v208
	v_cmp_gt_u32_e32 vcc, s70, v209
	s_nop 1
	v_cndmask_b32_e32 v69, v225, v69, vcc
	v_add_u32_e32 v209, 6, v208
	v_cmp_gt_u32_e32 vcc, s70, v209
	s_nop 1
	v_cndmask_b32_e32 v86, v225, v86, vcc
	v_add_u32_e32 v209, 38, v208
	v_cmp_gt_u32_e32 vcc, s70, v209
	s_nop 1
	v_cndmask_b32_e32 v70, v225, v70, vcc
	v_add_u32_e32 v209, 7, v208
	v_cmp_gt_u32_e32 vcc, s70, v209
	s_nop 1
	v_cndmask_b32_e32 v87, v225, v87, vcc
	v_add_u32_e32 v209, 39, v208
	v_cmp_gt_u32_e32 vcc, s70, v209
	s_nop 1
	v_cndmask_b32_e32 v71, v225, v71, vcc
	v_add_u32_e32 v209, 16, v208
	v_cmp_gt_u32_e32 vcc, s70, v209
	s_nop 1
	v_cndmask_b32_e32 v88, v225, v88, vcc
	v_add_u32_e32 v209, 48, v208
	v_cmp_gt_u32_e32 vcc, s70, v209
	s_nop 1
	v_cndmask_b32_e32 v72, v225, v72, vcc
	v_add_u32_e32 v209, 17, v208
	v_cmp_gt_u32_e32 vcc, s70, v209
	s_nop 1
	v_cndmask_b32_e32 v89, v225, v89, vcc
	v_add_u32_e32 v209, 49, v208
	v_cmp_gt_u32_e32 vcc, s70, v209
	s_nop 1
	v_cndmask_b32_e32 v73, v225, v73, vcc
	v_add_u32_e32 v209, 18, v208
	v_cmp_gt_u32_e32 vcc, s70, v209
	s_nop 1
	v_cndmask_b32_e32 v90, v225, v90, vcc
	v_add_u32_e32 v209, 50, v208
	v_cmp_gt_u32_e32 vcc, s70, v209
	s_nop 1
	v_cndmask_b32_e32 v74, v225, v74, vcc
	v_add_u32_e32 v209, 19, v208
	v_cmp_gt_u32_e32 vcc, s70, v209
	s_nop 1
	v_cndmask_b32_e32 v91, v225, v91, vcc
	v_add_u32_e32 v209, 51, v208
	v_cmp_gt_u32_e32 vcc, s70, v209
	s_nop 1
	v_cndmask_b32_e32 v75, v225, v75, vcc
	v_add_u32_e32 v209, 20, v208
	v_cmp_gt_u32_e32 vcc, s70, v209
	s_nop 1
	v_cndmask_b32_e32 v92, v225, v92, vcc
	v_add_u32_e32 v209, 52, v208
	v_cmp_gt_u32_e32 vcc, s70, v209
	s_nop 1
	v_cndmask_b32_e32 v76, v225, v76, vcc
	v_add_u32_e32 v209, 21, v208
	v_cmp_gt_u32_e32 vcc, s70, v209
	s_nop 1
	v_cndmask_b32_e32 v93, v225, v93, vcc
	v_add_u32_e32 v209, 53, v208
	v_cmp_gt_u32_e32 vcc, s70, v209
	s_nop 1
	v_cndmask_b32_e32 v77, v225, v77, vcc
	v_add_u32_e32 v209, 22, v208
	v_cmp_gt_u32_e32 vcc, s70, v209
	s_nop 1
	v_cndmask_b32_e32 v94, v225, v94, vcc
	v_add_u32_e32 v209, 54, v208
	v_cmp_gt_u32_e32 vcc, s70, v209
	s_nop 1
	v_cndmask_b32_e32 v78, v225, v78, vcc
	v_add_u32_e32 v209, 23, v208
	v_cmp_gt_u32_e32 vcc, s70, v209
	s_nop 1
	v_cndmask_b32_e32 v95, v225, v95, vcc
	v_add_u32_e32 v209, 55, v208
	v_cmp_gt_u32_e32 vcc, s70, v209
	s_nop 1
	v_cndmask_b32_e32 v79, v225, v79, vcc
